# norm phases, context rows: the 8 split-K share loads per 512-column chunk issued together (16 loads) instead of 8 load-wait-add round trips; same add order
# baseline (speedup 1.0000x reference)
; __device__ __forceinline__ unsigned cvt_pk_bf16(float lo, float hi) { unsigned r; asm volatile("v_cvt_pk_bf16_f32 %0, %1, %2" : "=v"(r) : "v"(lo), "v"(hi)); return r; }
; __device__ void phase_norm(const Ctx& c, const void* xlat, bool lat_f32, const void* xctx, bool ctx_f32, const float* __restrict__ g, const float* __restrict__ mod, int sh_off, int sc_off,
;                            bf16_t* __restrict__ dst, int nrows, const float* part) {
;     ...
;         if (part != nullptr && row >= TL) {
;             const float* pr = part + (size_t)(row - TL) * DM + c.lane * 8; bf16_t* xo = XW + (size_t)row * DM + c.lane * 8;
; #pragma unroll
;             for (int i = 0; i < 4; ++i) {
; #pragma unroll
;                 for (int sp = 0; sp < 8; ++sp) { v[2 * i] += *(const f32x4*)(pr + (size_t)sp * TC * DM + i * 512); v[2 * i + 1] += *(const f32x4*)(pr + (size_t)sp * TC * DM + i * 512 + 4); }
;                 u32x4 w; w.x = cvt_pk_bf16(v[2 * i][0], v[2 * i][1]); w.y = cvt_pk_bf16(v[2 * i][2], v[2 * i][3]); w.z = cvt_pk_bf16(v[2 * i + 1][0], v[2 * i + 1][1]); w.w = cvt_pk_bf16(v[2 * i + 1][2], v[2 * i + 1][3]);
;                 *(u32x4*)(xo + i * 512) = w;
;                 __builtin_amdgcn_sched_barrier(0); }
.LBB0_797:
	v_lshlrev_b64 v[52:53], 13, v[34:35]
	v_lshl_add_u64 v[54:55], v[40:41], 0, v[52:53]
	v_mov_b64_e32 v[168:169], v[54:55]
	v_mov_b32_e32 v171, 0
	v_mov_b32_e32 v170, 0x0
	v_lshl_add_u64 v[172:173], v[168:169], 0, v[170:171]
	global_load_dwordx4 v[104:107], v[172:173], off
	global_load_dwordx4 v[108:111], v[172:173], off offset:16
	v_mov_b32_e32 v170, 0x800000
	v_lshl_add_u64 v[172:173], v[168:169], 0, v[170:171]
	global_load_dwordx4 v[112:115], v[172:173], off
	global_load_dwordx4 v[116:119], v[172:173], off offset:16
	v_mov_b32_e32 v170, 0x1000000
	v_lshl_add_u64 v[172:173], v[168:169], 0, v[170:171]
	global_load_dwordx4 v[120:123], v[172:173], off
	global_load_dwordx4 v[124:127], v[172:173], off offset:16
	v_mov_b32_e32 v170, 0x1800000
	v_lshl_add_u64 v[172:173], v[168:169], 0, v[170:171]
	global_load_dwordx4 v[128:131], v[172:173], off
	global_load_dwordx4 v[132:135], v[172:173], off offset:16
	v_mov_b32_e32 v170, 0x2000000
	v_lshl_add_u64 v[172:173], v[168:169], 0, v[170:171]
	global_load_dwordx4 v[136:139], v[172:173], off
	global_load_dwordx4 v[140:143], v[172:173], off offset:16
	v_mov_b32_e32 v170, 0x2800000
	v_lshl_add_u64 v[172:173], v[168:169], 0, v[170:171]
	global_load_dwordx4 v[144:147], v[172:173], off
	global_load_dwordx4 v[148:151], v[172:173], off offset:16
	v_mov_b32_e32 v170, 0x3000000
	v_lshl_add_u64 v[172:173], v[168:169], 0, v[170:171]
	global_load_dwordx4 v[152:155], v[172:173], off
	global_load_dwordx4 v[156:159], v[172:173], off offset:16
	v_mov_b32_e32 v170, 0x3800000
	v_lshl_add_u64 v[172:173], v[168:169], 0, v[170:171]
	global_load_dwordx4 v[160:163], v[172:173], off
	global_load_dwordx4 v[164:167], v[172:173], off offset:16
	s_waitcnt vmcnt(0)
	v_mov_b64_e32 v[56:57], v[108:109]
	v_mov_b64_e32 v[58:59], v[110:111]
	v_mov_b64_e32 v[60:61], v[104:105]
	v_mov_b64_e32 v[62:63], v[106:107]
	v_add_co_u32_e32 v72, vcc, s44, v54
	s_mov_b64 s[96:97], 0x800000
	s_nop 0
	v_addc_co_u32_e32 v73, vcc, 0, v55, vcc
	s_mov_b32 s95, 0x1000000
	v_mov_b32_e32 v33, v35
	v_lshlrev_b64 v[52:53], 12, v[32:33]
	v_lshl_add_u64 v[52:53], v[38:39], 0, v[52:53]
	s_nop 0
	v_pk_add_f32 v[64:65], v[56:57], v[24:25]
	v_add_co_u32_e32 v56, vcc, s45, v54
	v_pk_add_f32 v[60:61], v[60:61], v[28:29]
	v_lshl_add_u64 v[28:29], v[54:55], 0, s[96:97]
	v_addc_co_u32_e32 v57, vcc, 0, v55, vcc
	v_pk_add_f32 v[62:63], v[62:63], v[30:31]
	v_pk_add_f32 v[58:59], v[58:59], v[26:27]
	v_mov_b64_e32 v[24:25], v[112:113]
	v_mov_b64_e32 v[26:27], v[114:115]
	s_nop 0
	v_mov_b64_e32 v[28:29], v[116:117]
	v_mov_b64_e32 v[30:31], v[118:119]
	v_add_co_u32_e32 v70, vcc, s95, v54
	s_mov_b64 s[96:97], 0x1000000
	s_nop 0
	v_addc_co_u32_e32 v71, vcc, 0, v55, vcc
	s_mov_b32 s95, 0x1800000
	s_nop 0
	v_pk_add_f32 v[62:63], v[62:63], v[26:27]
	s_nop 0
	v_pk_add_f32 v[66:67], v[58:59], v[30:31]
	v_add_co_u32_e32 v58, vcc, s82, v54
	v_pk_add_f32 v[64:65], v[64:65], v[28:29]
	v_lshl_add_u64 v[28:29], v[54:55], 0, s[96:97]
	v_addc_co_u32_e32 v59, vcc, 0, v55, vcc
	v_pk_add_f32 v[60:61], v[60:61], v[24:25]
	v_mov_b64_e32 v[24:25], v[120:121]
	v_mov_b64_e32 v[26:27], v[122:123]
	s_nop 0
	v_mov_b64_e32 v[28:29], v[124:125]
	v_mov_b64_e32 v[30:31], v[126:127]
	v_add_co_u32_e32 v74, vcc, s95, v54
	s_mov_b64 s[96:97], 0x1800000
	s_nop 0
	v_addc_co_u32_e32 v75, vcc, 0, v55, vcc
	s_brev_b32 s95, 64
	s_nop 0
	v_pk_add_f32 v[68:69], v[60:61], v[24:25]
	v_add_co_u32_e32 v60, vcc, s83, v54
	s_nop 0
	v_pk_add_f32 v[64:65], v[64:65], v[28:29]
	v_lshl_add_u64 v[28:29], v[54:55], 0, s[96:97]
	v_addc_co_u32_e32 v61, vcc, 0, v55, vcc
	v_pk_add_f32 v[62:63], v[62:63], v[26:27]
	v_pk_add_f32 v[66:67], v[66:67], v[30:31]
	v_mov_b64_e32 v[24:25], v[128:129]
	v_mov_b64_e32 v[26:27], v[130:131]
	s_nop 0
	v_mov_b64_e32 v[28:29], v[132:133]
	v_mov_b64_e32 v[30:31], v[134:135]
	v_add_co_u32_e32 v76, vcc, s95, v54
	s_mov_b64 s[96:97], 0x2000000
	s_nop 0
	v_addc_co_u32_e32 v77, vcc, 0, v55, vcc
	s_mov_b32 s95, 0x2800000
	s_nop 0
	v_pk_add_f32 v[78:79], v[62:63], v[26:27]
	v_add_co_u32_e32 v62, vcc, s85, v54
	s_nop 0
	v_pk_add_f32 v[64:65], v[64:65], v[28:29]
	v_lshl_add_u64 v[28:29], v[54:55], 0, s[96:97]
	v_addc_co_u32_e32 v63, vcc, 0, v55, vcc
	v_pk_add_f32 v[68:69], v[68:69], v[24:25]
	v_pk_add_f32 v[66:67], v[66:67], v[30:31]
	v_mov_b64_e32 v[24:25], v[136:137]
	v_mov_b64_e32 v[26:27], v[138:139]
	s_nop 0
	v_mov_b64_e32 v[28:29], v[140:141]
	v_mov_b64_e32 v[30:31], v[142:143]
	s_mov_b64 s[96:97], 0x2800000
	s_nop 0
	v_pk_add_f32 v[80:81], v[78:79], v[26:27]
	v_add_co_u32_e32 v78, vcc, s95, v54
	s_nop 0
	v_pk_add_f32 v[82:83], v[64:65], v[28:29]
	v_addc_co_u32_e32 v79, vcc, 0, v55, vcc
	v_add_co_u32_e32 v64, vcc, s86, v54
	v_lshl_add_u64 v[28:29], v[54:55], 0, s[96:97]
	s_nop 0
	v_addc_co_u32_e32 v65, vcc, 0, v55, vcc
	v_pk_add_f32 v[68:69], v[68:69], v[24:25]
	v_pk_add_f32 v[66:67], v[66:67], v[30:31]
	v_mov_b64_e32 v[24:25], v[144:145]
	v_mov_b64_e32 v[26:27], v[146:147]
	s_nop 0
	v_mov_b64_e32 v[28:29], v[148:149]
	v_mov_b64_e32 v[30:31], v[150:151]
	s_mov_b32 s95, 0x3000000
	s_mov_b64 s[96:97], 0x3000000
	s_nop 0
	v_pk_add_f32 v[92:93], v[80:81], v[26:27]
	v_add_co_u32_e32 v80, vcc, s95, v54
	s_nop 0
	v_pk_add_f32 v[94:95], v[66:67], v[30:31]
	v_addc_co_u32_e32 v81, vcc, 0, v55, vcc
	v_add_co_u32_e32 v66, vcc, s87, v54
	v_pk_add_f32 v[82:83], v[82:83], v[28:29]
	v_lshl_add_u64 v[28:29], v[54:55], 0, s[96:97]
	v_addc_co_u32_e32 v67, vcc, 0, v55, vcc
	v_pk_add_f32 v[68:69], v[68:69], v[24:25]
	v_mov_b64_e32 v[24:25], v[152:153]
	v_mov_b64_e32 v[26:27], v[154:155]
	s_nop 0
	v_mov_b64_e32 v[28:29], v[156:157]
	v_mov_b64_e32 v[30:31], v[158:159]
	s_mov_b32 s95, 0x3800000
	s_mov_b64 s[96:97], 0x3800000
; __device__ __forceinline__ unsigned cvt_pk_bf16(float lo, float hi) { unsigned r; asm volatile("v_cvt_pk_bf16_f32 %0, %1, %2" : "=v"(r) : "v"(lo), "v"(hi)); return r; }
; __device__ void phase_norm(const Ctx& c, const void* xlat, bool lat_f32, const void* xctx, bool ctx_f32, const float* __restrict__ g, const float* __restrict__ mod, int sh_off, int sc_off,
;                            bf16_t* __restrict__ dst, int nrows, const float* part) {
;     ...
;         if (part != nullptr && row >= TL) {
;             const float* pr = part + (size_t)(row - TL) * DM + c.lane * 8; bf16_t* xo = XW + (size_t)row * DM + c.lane * 8;
; #pragma unroll
;             for (int i = 0; i < 4; ++i) {
; #pragma unroll
;                 for (int sp = 0; sp < 8; ++sp) { v[2 * i] += *(const f32x4*)(pr + (size_t)sp * TC * DM + i * 512); v[2 * i + 1] += *(const f32x4*)(pr + (size_t)sp * TC * DM + i * 512 + 4); }
;                 u32x4 w; w.x = cvt_pk_bf16(v[2 * i][0], v[2 * i][1]); w.y = cvt_pk_bf16(v[2 * i][2], v[2 * i][3]); w.z = cvt_pk_bf16(v[2 * i + 1][0], v[2 * i + 1][1]); w.w = cvt_pk_bf16(v[2 * i + 1][2], v[2 * i + 1][3]);
;                 *(u32x4*)(xo + i * 512) = w;
;                 __builtin_amdgcn_sched_barrier(0); }
	s_nop 0
	v_pk_add_f32 v[98:99], v[68:69], v[24:25]
	s_nop 0
	v_pk_add_f32 v[102:103], v[82:83], v[28:29]
	v_add_co_u32_e32 v82, vcc, s95, v54
	v_pk_add_f32 v[96:97], v[92:93], v[26:27]
	s_nop 0
	v_addc_co_u32_e32 v83, vcc, 0, v55, vcc
	v_add_co_u32_e32 v68, vcc, s88, v54
	v_pk_add_f32 v[100:101], v[94:95], v[30:31]
	s_nop 0
	v_addc_co_u32_e32 v69, vcc, 0, v55, vcc
	v_lshl_add_u64 v[28:29], v[54:55], 0, s[96:97]
	v_mov_b64_e32 v[24:25], v[160:161]
	v_mov_b64_e32 v[26:27], v[162:163]
	v_mov_b64_e32 v[92:93], v[164:165]
	v_mov_b64_e32 v[94:95], v[166:167]
	s_nop 0
	v_pk_add_f32 v[30:31], v[96:97], v[26:27]
	v_pk_add_f32 v[28:29], v[98:99], v[24:25]
	s_nop 0
	v_pk_add_f32 v[26:27], v[100:101], v[94:95]
	v_pk_add_f32 v[24:25], v[102:103], v[92:93]
	v_cvt_pk_bf16_f32 v92, v28, v29
	v_cvt_pk_bf16_f32 v93, v30, v31
	s_nop 0
	v_cvt_pk_bf16_f32 v94, v24, v25
	v_cvt_pk_bf16_f32 v95, v26, v27
	global_store_dwordx4 v[52:53], v[92:95], off
	v_mov_b32_e32 v170, 0x800
	v_lshl_add_u64 v[172:173], v[168:169], 0, v[170:171]
	global_load_dwordx4 v[104:107], v[172:173], off
	global_load_dwordx4 v[108:111], v[172:173], off offset:16
	v_mov_b32_e32 v170, 0x800800
	v_lshl_add_u64 v[172:173], v[168:169], 0, v[170:171]
	global_load_dwordx4 v[112:115], v[172:173], off
	global_load_dwordx4 v[116:119], v[172:173], off offset:16
	v_mov_b32_e32 v170, 0x1000800
	v_lshl_add_u64 v[172:173], v[168:169], 0, v[170:171]
	global_load_dwordx4 v[120:123], v[172:173], off
	global_load_dwordx4 v[124:127], v[172:173], off offset:16
	v_mov_b32_e32 v170, 0x1800800
	v_lshl_add_u64 v[172:173], v[168:169], 0, v[170:171]
	global_load_dwordx4 v[128:131], v[172:173], off
	global_load_dwordx4 v[132:135], v[172:173], off offset:16
	v_mov_b32_e32 v170, 0x2000800
	v_lshl_add_u64 v[172:173], v[168:169], 0, v[170:171]
	global_load_dwordx4 v[136:139], v[172:173], off
	global_load_dwordx4 v[140:143], v[172:173], off offset:16
	v_mov_b32_e32 v170, 0x2800800
	v_lshl_add_u64 v[172:173], v[168:169], 0, v[170:171]
	global_load_dwordx4 v[144:147], v[172:173], off
	global_load_dwordx4 v[148:151], v[172:173], off offset:16
	v_mov_b32_e32 v170, 0x3000800
	v_lshl_add_u64 v[172:173], v[168:169], 0, v[170:171]
	global_load_dwordx4 v[152:155], v[172:173], off
	global_load_dwordx4 v[156:159], v[172:173], off offset:16
	v_mov_b32_e32 v170, 0x3800800
	v_lshl_add_u64 v[172:173], v[168:169], 0, v[170:171]
	global_load_dwordx4 v[160:163], v[172:173], off
	global_load_dwordx4 v[164:167], v[172:173], off offset:16
	s_waitcnt vmcnt(0)
	v_mov_b64_e32 v[92:93], v[108:109]
	v_mov_b64_e32 v[94:95], v[110:111]
	s_nop 0
	v_mov_b64_e32 v[96:97], v[104:105]
	v_mov_b64_e32 v[98:99], v[106:107]
	s_mov_b64 s[96:97], 0x800800
	s_nop 0
	v_pk_add_f32 v[94:95], v[94:95], v[18:19]
	s_nop 0
	v_pk_add_f32 v[96:97], v[96:97], v[20:21]
	v_lshl_add_u64 v[20:21], v[54:55], 0, s[96:97]
	v_pk_add_f32 v[98:99], v[98:99], v[22:23]
	v_pk_add_f32 v[92:93], v[92:93], v[16:17]
	v_mov_b64_e32 v[16:17], v[112:113]
	v_mov_b64_e32 v[18:19], v[114:115]
	s_nop 0
	v_mov_b64_e32 v[20:21], v[116:117]
	v_mov_b64_e32 v[22:23], v[118:119]
	s_mov_b64 s[96:97], 0x1000800
	s_nop 0
	v_pk_add_f32 v[72:73], v[98:99], v[18:19]
	s_nop 0
	v_pk_add_f32 v[92:93], v[92:93], v[20:21]
	v_lshl_add_u64 v[20:21], v[54:55], 0, s[96:97]
	v_pk_add_f32 v[96:97], v[96:97], v[16:17]
	v_pk_add_f32 v[94:95], v[94:95], v[22:23]
	v_mov_b64_e32 v[16:17], v[120:121]
	v_mov_b64_e32 v[18:19], v[122:123]
	s_nop 0
	v_mov_b64_e32 v[20:21], v[124:125]
	v_mov_b64_e32 v[22:23], v[126:127]
	s_mov_b64 s[96:97], 0x1800800
	s_nop 0
	v_pk_add_f32 v[70:71], v[72:73], v[18:19]
	s_nop 0
	v_pk_add_f32 v[92:93], v[92:93], v[20:21]
	v_lshl_add_u64 v[20:21], v[54:55], 0, s[96:97]
	v_pk_add_f32 v[72:73], v[96:97], v[16:17]
	v_pk_add_f32 v[94:95], v[94:95], v[22:23]
	v_mov_b64_e32 v[16:17], v[128:129]
	v_mov_b64_e32 v[18:19], v[130:131]
	s_nop 0
	v_mov_b64_e32 v[20:21], v[132:133]
	v_mov_b64_e32 v[22:23], v[134:135]
	s_nop 0
	v_pk_add_f32 v[70:71], v[70:71], v[18:19]
	s_nop 0
	v_pk_add_f32 v[92:93], v[92:93], v[20:21]
	v_lshl_add_u64 v[20:21], v[54:55], 0, s[16:17]
	v_pk_add_f32 v[72:73], v[72:73], v[16:17]
	v_pk_add_f32 v[74:75], v[94:95], v[22:23]
	v_mov_b64_e32 v[16:17], v[136:137]
	v_mov_b64_e32 v[18:19], v[138:139]
	s_nop 0
	v_mov_b64_e32 v[20:21], v[140:141]
	v_mov_b64_e32 v[22:23], v[142:143]
	s_nop 0
	v_pk_add_f32 v[70:71], v[70:71], v[18:19]
	s_nop 0
	v_pk_add_f32 v[76:77], v[92:93], v[20:21]
	v_lshl_add_u64 v[20:21], v[54:55], 0, s[18:19]
	v_pk_add_f32 v[72:73], v[72:73], v[16:17]
	v_pk_add_f32 v[74:75], v[74:75], v[22:23]
	v_mov_b64_e32 v[16:17], v[144:145]
	v_mov_b64_e32 v[18:19], v[146:147]
	s_nop 0
	v_mov_b64_e32 v[20:21], v[148:149]
	v_mov_b64_e32 v[22:23], v[150:151]
	s_nop 0
	v_pk_add_f32 v[70:71], v[70:71], v[18:19]
	s_nop 0
	v_pk_add_f32 v[76:77], v[76:77], v[20:21]
	v_lshl_add_u64 v[20:21], v[54:55], 0, s[20:21]
	v_pk_add_f32 v[72:73], v[72:73], v[16:17]
	v_pk_add_f32 v[74:75], v[74:75], v[22:23]
	v_mov_b64_e32 v[16:17], v[152:153]
	v_mov_b64_e32 v[18:19], v[154:155]
	s_nop 0
	v_mov_b64_e32 v[20:21], v[156:157]
	v_mov_b64_e32 v[22:23], v[158:159]
	s_nop 0
	v_pk_add_f32 v[78:79], v[70:71], v[18:19]
	v_pk_add_f32 v[80:81], v[72:73], v[16:17]
	s_nop 0
	v_pk_add_f32 v[76:77], v[76:77], v[20:21]
	v_lshl_add_u64 v[20:21], v[54:55], 0, s[22:23]
	v_mov_b64_e32 v[16:17], v[160:161]
	v_mov_b64_e32 v[18:19], v[162:163]
	v_mov_b64_e32 v[70:71], v[164:165]
	v_mov_b64_e32 v[72:73], v[166:167]
	v_pk_add_f32 v[74:75], v[74:75], v[22:23]
	s_nop 0
	v_pk_add_f32 v[22:23], v[78:79], v[18:19]
	v_pk_add_f32 v[20:21], v[80:81], v[16:17]
	s_nop 0
	v_pk_add_f32 v[18:19], v[74:75], v[72:73]
; __device__ __forceinline__ unsigned cvt_pk_bf16(float lo, float hi) { unsigned r; asm volatile("v_cvt_pk_bf16_f32 %0, %1, %2" : "=v"(r) : "v"(lo), "v"(hi)); return r; }
; __device__ void phase_norm(const Ctx& c, const void* xlat, bool lat_f32, const void* xctx, bool ctx_f32, const float* __restrict__ g, const float* __restrict__ mod, int sh_off, int sc_off,
;                            bf16_t* __restrict__ dst, int nrows, const float* part) {
;     ...
;         if (part != nullptr && row >= TL) {
;             const float* pr = part + (size_t)(row - TL) * DM + c.lane * 8; bf16_t* xo = XW + (size_t)row * DM + c.lane * 8;
; #pragma unroll
;             for (int i = 0; i < 4; ++i) {
; #pragma unroll
;                 for (int sp = 0; sp < 8; ++sp) { v[2 * i] += *(const f32x4*)(pr + (size_t)sp * TC * DM + i * 512); v[2 * i + 1] += *(const f32x4*)(pr + (size_t)sp * TC * DM + i * 512 + 4); }
;                 u32x4 w; w.x = cvt_pk_bf16(v[2 * i][0], v[2 * i][1]); w.y = cvt_pk_bf16(v[2 * i][2], v[2 * i][3]); w.z = cvt_pk_bf16(v[2 * i + 1][0], v[2 * i + 1][1]); w.w = cvt_pk_bf16(v[2 * i + 1][2], v[2 * i + 1][3]);
;                 *(u32x4*)(xo + i * 512) = w;
;                 __builtin_amdgcn_sched_barrier(0); }
	v_pk_add_f32 v[16:17], v[76:77], v[70:71]
	v_cvt_pk_bf16_f32 v70, v20, v21
	v_cvt_pk_bf16_f32 v71, v22, v23
	s_nop 0
	v_cvt_pk_bf16_f32 v72, v16, v17
	v_cvt_pk_bf16_f32 v73, v18, v19
	global_store_dwordx4 v[52:53], v[70:73], off offset:1024
	s_nop 1
	v_add_co_u32_e32 v70, vcc, s43, v54
	v_lshl_add_u64 v[76:77], v[54:55], 0, s[4:5]
	s_nop 0
	v_addc_co_u32_e32 v71, vcc, 0, v55, vcc
	v_mov_b32_e32 v170, 0x1000
	v_lshl_add_u64 v[172:173], v[168:169], 0, v[170:171]
	global_load_dwordx4 v[104:107], v[172:173], off
	global_load_dwordx4 v[108:111], v[172:173], off offset:16
	v_mov_b32_e32 v170, 0x801000
	v_lshl_add_u64 v[172:173], v[168:169], 0, v[170:171]
	global_load_dwordx4 v[112:115], v[172:173], off
	global_load_dwordx4 v[116:119], v[172:173], off offset:16
	v_mov_b32_e32 v170, 0x1001000
	v_lshl_add_u64 v[172:173], v[168:169], 0, v[170:171]
	global_load_dwordx4 v[120:123], v[172:173], off
	global_load_dwordx4 v[124:127], v[172:173], off offset:16
	v_mov_b32_e32 v170, 0x1801000
	v_lshl_add_u64 v[172:173], v[168:169], 0, v[170:171]
	global_load_dwordx4 v[128:131], v[172:173], off
	global_load_dwordx4 v[132:135], v[172:173], off offset:16
	v_mov_b32_e32 v170, 0x2001000
	v_lshl_add_u64 v[172:173], v[168:169], 0, v[170:171]
	global_load_dwordx4 v[136:139], v[172:173], off
	global_load_dwordx4 v[140:143], v[172:173], off offset:16
	v_mov_b32_e32 v170, 0x2801000
	v_lshl_add_u64 v[172:173], v[168:169], 0, v[170:171]
	global_load_dwordx4 v[144:147], v[172:173], off
	global_load_dwordx4 v[148:151], v[172:173], off offset:16
	v_mov_b32_e32 v170, 0x3001000
	v_lshl_add_u64 v[172:173], v[168:169], 0, v[170:171]
	global_load_dwordx4 v[152:155], v[172:173], off
	global_load_dwordx4 v[156:159], v[172:173], off offset:16
	v_mov_b32_e32 v170, 0x3801000
	v_lshl_add_u64 v[172:173], v[168:169], 0, v[170:171]
	global_load_dwordx4 v[160:163], v[172:173], off
	global_load_dwordx4 v[164:167], v[172:173], off offset:16
	s_waitcnt vmcnt(0)
	v_mov_b64_e32 v[72:73], v[104:105]
	v_mov_b64_e32 v[74:75], v[106:107]
	s_nop 0
	v_mov_b64_e32 v[76:77], v[108:109]
	v_mov_b64_e32 v[78:79], v[110:111]
	s_nop 0
	v_pk_add_f32 v[74:75], v[74:75], v[10:11]
	s_nop 0
	v_pk_add_f32 v[76:77], v[76:77], v[12:13]
	v_lshl_add_u64 v[12:13], v[54:55], 0, s[24:25]
	v_pk_add_f32 v[72:73], v[72:73], v[8:9]
	v_pk_add_f32 v[78:79], v[78:79], v[14:15]
	v_mov_b64_e32 v[8:9], v[112:113]
	v_mov_b64_e32 v[10:11], v[114:115]
	s_nop 0
	v_mov_b64_e32 v[12:13], v[116:117]
	v_mov_b64_e32 v[14:15], v[118:119]
	s_nop 0
	v_pk_add_f32 v[74:75], v[74:75], v[10:11]
	s_nop 0
	v_pk_add_f32 v[76:77], v[76:77], v[12:13]
	v_lshl_add_u64 v[12:13], v[54:55], 0, s[26:27]
	v_pk_add_f32 v[72:73], v[72:73], v[8:9]
	v_pk_add_f32 v[78:79], v[78:79], v[14:15]
	v_mov_b64_e32 v[8:9], v[120:121]
	v_mov_b64_e32 v[10:11], v[122:123]
	s_nop 0
	v_mov_b64_e32 v[12:13], v[124:125]
	v_mov_b64_e32 v[14:15], v[126:127]
	s_nop 0
	v_pk_add_f32 v[74:75], v[74:75], v[10:11]
	s_nop 0
	v_pk_add_f32 v[76:77], v[76:77], v[12:13]
	v_lshl_add_u64 v[12:13], v[54:55], 0, s[28:29]
	v_pk_add_f32 v[72:73], v[72:73], v[8:9]
	v_pk_add_f32 v[78:79], v[78:79], v[14:15]
	v_mov_b64_e32 v[8:9], v[128:129]
	v_mov_b64_e32 v[10:11], v[130:131]
	s_nop 0
	v_mov_b64_e32 v[12:13], v[132:133]
	v_mov_b64_e32 v[14:15], v[134:135]
	s_nop 0
	v_pk_add_f32 v[74:75], v[74:75], v[10:11]
	s_nop 0
	v_pk_add_f32 v[76:77], v[76:77], v[12:13]
	v_lshl_add_u64 v[12:13], v[54:55], 0, s[30:31]
	v_pk_add_f32 v[72:73], v[72:73], v[8:9]
	v_pk_add_f32 v[78:79], v[78:79], v[14:15]
	v_mov_b64_e32 v[8:9], v[136:137]
	v_mov_b64_e32 v[10:11], v[138:139]
	s_nop 0
	v_mov_b64_e32 v[12:13], v[140:141]
	v_mov_b64_e32 v[14:15], v[142:143]
	s_nop 0
	v_pk_add_f32 v[74:75], v[74:75], v[10:11]
	s_nop 0
	v_pk_add_f32 v[76:77], v[76:77], v[12:13]
	v_lshl_add_u64 v[12:13], v[54:55], 0, s[34:35]
	v_pk_add_f32 v[72:73], v[72:73], v[8:9]
	v_pk_add_f32 v[78:79], v[78:79], v[14:15]
	v_mov_b64_e32 v[8:9], v[144:145]
	v_mov_b64_e32 v[10:11], v[146:147]
	s_nop 0
	v_mov_b64_e32 v[12:13], v[148:149]
	v_mov_b64_e32 v[14:15], v[150:151]
	s_nop 0
	v_pk_add_f32 v[74:75], v[74:75], v[10:11]
	s_nop 0
	v_pk_add_f32 v[76:77], v[76:77], v[12:13]
	v_lshl_add_u64 v[12:13], v[54:55], 0, s[46:47]
	v_pk_add_f32 v[72:73], v[72:73], v[8:9]
	v_pk_add_f32 v[78:79], v[78:79], v[14:15]
	v_mov_b64_e32 v[8:9], v[152:153]
	v_mov_b64_e32 v[10:11], v[154:155]
	s_nop 0
	v_mov_b64_e32 v[12:13], v[156:157]
	v_mov_b64_e32 v[14:15], v[158:159]
	s_nop 0
	v_pk_add_f32 v[74:75], v[74:75], v[10:11]
	s_nop 0
	v_pk_add_f32 v[76:77], v[76:77], v[12:13]
	v_lshl_add_u64 v[12:13], v[54:55], 0, s[48:49]
	v_pk_add_f32 v[72:73], v[72:73], v[8:9]
	v_pk_add_f32 v[78:79], v[78:79], v[14:15]
	v_mov_b64_e32 v[8:9], v[160:161]
	v_mov_b64_e32 v[10:11], v[162:163]
	s_nop 0
	v_mov_b64_e32 v[12:13], v[164:165]
	v_mov_b64_e32 v[14:15], v[166:167]
	s_nop 0
	v_pk_add_f32 v[10:11], v[74:75], v[10:11]
	v_pk_add_f32 v[8:9], v[72:73], v[8:9]
	s_nop 0
	v_pk_add_f32 v[14:15], v[78:79], v[14:15]
	v_pk_add_f32 v[12:13], v[76:77], v[12:13]
	v_cvt_pk_bf16_f32 v72, v8, v9
	v_cvt_pk_bf16_f32 v73, v10, v11
	s_nop 0
	v_cvt_pk_bf16_f32 v74, v12, v13
	v_cvt_pk_bf16_f32 v75, v14, v15
	global_store_dwordx4 v[52:53], v[72:75], off offset:2048
	s_nop 1
	v_lshl_add_u64 v[74:75], v[54:55], 0, s[6:7]
	v_mov_b32_e32 v170, 0x1800
	v_lshl_add_u64 v[172:173], v[168:169], 0, v[170:171]
	global_load_dwordx4 v[104:107], v[172:173], off
	global_load_dwordx4 v[108:111], v[172:173], off offset:16
	v_mov_b32_e32 v170, 0x801800
	v_lshl_add_u64 v[172:173], v[168:169], 0, v[170:171]
	global_load_dwordx4 v[112:115], v[172:173], off
	global_load_dwordx4 v[116:119], v[172:173], off offset:16
	v_mov_b32_e32 v170, 0x1001800
	v_lshl_add_u64 v[172:173], v[168:169], 0, v[170:171]
	global_load_dwordx4 v[120:123], v[172:173], off
	global_load_dwordx4 v[124:127], v[172:173], off offset:16
	v_mov_b32_e32 v170, 0x1801800
	v_lshl_add_u64 v[172:173], v[168:169], 0, v[170:171]
	global_load_dwordx4 v[128:131], v[172:173], off
	global_load_dwordx4 v[132:135], v[172:173], off offset:16
	v_mov_b32_e32 v170, 0x2001800
	v_lshl_add_u64 v[172:173], v[168:169], 0, v[170:171]
	global_load_dwordx4 v[136:139], v[172:173], off
	global_load_dwordx4 v[140:143], v[172:173], off offset:16
	v_mov_b32_e32 v170, 0x2801800
	v_lshl_add_u64 v[172:173], v[168:169], 0, v[170:171]
	global_load_dwordx4 v[144:147], v[172:173], off
	global_load_dwordx4 v[148:151], v[172:173], off offset:16
	v_mov_b32_e32 v170, 0x3001800
	v_lshl_add_u64 v[172:173], v[168:169], 0, v[170:171]
	global_load_dwordx4 v[152:155], v[172:173], off
	global_load_dwordx4 v[156:159], v[172:173], off offset:16
	v_mov_b32_e32 v170, 0x3801800
	v_lshl_add_u64 v[172:173], v[168:169], 0, v[170:171]
	global_load_dwordx4 v[160:163], v[172:173], off
	global_load_dwordx4 v[164:167], v[172:173], off offset:16
	s_waitcnt vmcnt(0)
; __device__ __forceinline__ unsigned cvt_pk_bf16(float lo, float hi) { unsigned r; asm volatile("v_cvt_pk_bf16_f32 %0, %1, %2" : "=v"(r) : "v"(lo), "v"(hi)); return r; }
; __device__ void phase_norm(const Ctx& c, const void* xlat, bool lat_f32, const void* xctx, bool ctx_f32, const float* __restrict__ g, const float* __restrict__ mod, int sh_off, int sc_off,
;                            bf16_t* __restrict__ dst, int nrows, const float* part) {
;     ...
;         if (part != nullptr && row >= TL) {
;             const float* pr = part + (size_t)(row - TL) * DM + c.lane * 8; bf16_t* xo = XW + (size_t)row * DM + c.lane * 8;
; #pragma unroll
;             for (int i = 0; i < 4; ++i) {
; #pragma unroll
;                 for (int sp = 0; sp < 8; ++sp) { v[2 * i] += *(const f32x4*)(pr + (size_t)sp * TC * DM + i * 512); v[2 * i + 1] += *(const f32x4*)(pr + (size_t)sp * TC * DM + i * 512 + 4); }
;                 u32x4 w; w.x = cvt_pk_bf16(v[2 * i][0], v[2 * i][1]); w.y = cvt_pk_bf16(v[2 * i][2], v[2 * i][3]); w.z = cvt_pk_bf16(v[2 * i + 1][0], v[2 * i + 1][1]); w.w = cvt_pk_bf16(v[2 * i + 1][2], v[2 * i + 1][3]);
;                 *(u32x4*)(xo + i * 512) = w;
;                 __builtin_amdgcn_sched_barrier(0); }
;         }
	v_mov_b64_e32 v[70:71], v[104:105]
	v_mov_b64_e32 v[72:73], v[106:107]
	s_nop 0
	v_mov_b64_e32 v[74:75], v[108:109]
	v_mov_b64_e32 v[76:77], v[110:111]
	s_nop 0
	v_pk_add_f32 v[72:73], v[72:73], v[2:3]
	s_nop 0
	v_pk_add_f32 v[74:75], v[74:75], v[4:5]
	v_lshl_add_u64 v[4:5], v[54:55], 0, s[50:51]
	v_pk_add_f32 v[70:71], v[70:71], v[0:1]
	v_pk_add_f32 v[76:77], v[76:77], v[6:7]
	v_mov_b64_e32 v[0:1], v[112:113]
	v_mov_b64_e32 v[2:3], v[114:115]
	s_nop 0
	v_mov_b64_e32 v[4:5], v[116:117]
	v_mov_b64_e32 v[6:7], v[118:119]
	s_nop 0
	v_pk_add_f32 v[56:57], v[72:73], v[2:3]
	s_nop 0
	v_pk_add_f32 v[74:75], v[74:75], v[4:5]
	v_lshl_add_u64 v[4:5], v[54:55], 0, s[52:53]
	v_pk_add_f32 v[70:71], v[70:71], v[0:1]
	v_pk_add_f32 v[72:73], v[76:77], v[6:7]
	v_mov_b64_e32 v[0:1], v[120:121]
	v_mov_b64_e32 v[2:3], v[122:123]
	s_nop 0
	v_mov_b64_e32 v[4:5], v[124:125]
	v_mov_b64_e32 v[6:7], v[126:127]
	s_nop 0
	v_pk_add_f32 v[58:59], v[70:71], v[0:1]
	s_nop 0
	v_pk_add_f32 v[70:71], v[72:73], v[6:7]
	v_pk_add_f32 v[72:73], v[74:75], v[4:5]
	v_lshl_add_u64 v[4:5], v[54:55], 0, s[54:55]
	v_pk_add_f32 v[56:57], v[56:57], v[2:3]
	v_mov_b64_e32 v[0:1], v[128:129]
	v_mov_b64_e32 v[2:3], v[130:131]
	s_nop 0
	v_mov_b64_e32 v[4:5], v[132:133]
	v_mov_b64_e32 v[6:7], v[134:135]
	s_nop 0
	v_pk_add_f32 v[56:57], v[56:57], v[2:3]
	s_nop 0
	v_pk_add_f32 v[60:61], v[70:71], v[6:7]
	v_pk_add_f32 v[70:71], v[72:73], v[4:5]
	v_lshl_add_u64 v[4:5], v[54:55], 0, s[56:57]
	v_pk_add_f32 v[58:59], v[58:59], v[0:1]
	v_mov_b64_e32 v[0:1], v[136:137]
	v_mov_b64_e32 v[2:3], v[138:139]
	s_nop 0
	v_mov_b64_e32 v[4:5], v[140:141]
	v_mov_b64_e32 v[6:7], v[142:143]
	s_nop 0
	v_pk_add_f32 v[56:57], v[56:57], v[2:3]
	s_nop 0
	v_pk_add_f32 v[62:63], v[70:71], v[4:5]
	v_lshl_add_u64 v[4:5], v[54:55], 0, s[58:59]
	v_pk_add_f32 v[58:59], v[58:59], v[0:1]
	v_pk_add_f32 v[60:61], v[60:61], v[6:7]
	v_mov_b64_e32 v[0:1], v[144:145]
	v_mov_b64_e32 v[2:3], v[146:147]
	s_nop 0
	v_mov_b64_e32 v[4:5], v[148:149]
	v_mov_b64_e32 v[6:7], v[150:151]
	s_nop 0
	v_pk_add_f32 v[56:57], v[56:57], v[2:3]
	s_nop 0
	v_pk_add_f32 v[62:63], v[62:63], v[4:5]
	v_lshl_add_u64 v[4:5], v[54:55], 0, s[60:61]
	v_pk_add_f32 v[58:59], v[58:59], v[0:1]
	v_pk_add_f32 v[60:61], v[60:61], v[6:7]
	v_mov_b64_e32 v[0:1], v[152:153]
	v_mov_b64_e32 v[2:3], v[154:155]
	s_nop 0
	v_mov_b64_e32 v[4:5], v[156:157]
	v_mov_b64_e32 v[6:7], v[158:159]
	s_nop 0
	v_pk_add_f32 v[56:57], v[56:57], v[2:3]
	s_nop 0
	v_pk_add_f32 v[62:63], v[62:63], v[4:5]
	v_lshl_add_u64 v[4:5], v[54:55], 0, s[62:63]
	v_pk_add_f32 v[58:59], v[58:59], v[0:1]
	v_pk_add_f32 v[60:61], v[60:61], v[6:7]
	v_mov_b64_e32 v[0:1], v[160:161]
	v_mov_b64_e32 v[2:3], v[162:163]
	s_nop 0
	v_mov_b64_e32 v[4:5], v[164:165]
	v_mov_b64_e32 v[6:7], v[166:167]
	s_waitcnt vmcnt(1)
	v_pk_add_f32 v[2:3], v[56:57], v[2:3]
	v_pk_add_f32 v[0:1], v[58:59], v[0:1]
	s_waitcnt vmcnt(0)
	v_pk_add_f32 v[6:7], v[60:61], v[6:7]
	v_pk_add_f32 v[4:5], v[62:63], v[4:5]
	v_cvt_pk_bf16_f32 v54, v0, v1
	v_cvt_pk_bf16_f32 v55, v2, v3
	s_nop 0
	v_cvt_pk_bf16_f32 v56, v4, v5
	v_cvt_pk_bf16_f32 v57, v6, v7
	global_store_dwordx4 v[52:53], v[54:57], off offset:3072
	s_branch .LBB0_791

; __device__ __forceinline__ unsigned cvt_pk_bf16(float lo, float hi) { unsigned r; asm volatile("v_cvt_pk_bf16_f32 %0, %1, %2" : "=v"(r) : "v"(lo), "v"(hi)); return r; }
; __device__ __forceinline__ float lo_f(unsigned w) { return __uint_as_float(w << 16); }
; __device__ __forceinline__ float hi_f(unsigned w) { return __uint_as_float(w & 0xffff0000u); }
;     __device__ __forceinline__ bf16_t* bfp(size_t off) const { return (bf16_t*)(ws + off); }
; __device__ __forceinline__ void load_row32(f32x4 (&v)[8], const void* base, bool isf32, size_t rowoff, int lane) {
;     ...
;     else { const bf16_t* p = (const bf16_t*)base + rowoff + lane * 8;
; #pragma unroll
;         for (int i = 0; i < 4; ++i) { const u32x4 xb = *(const u32x4*)(p + i * 512);
;             v[2 * i] = (f32x4){lo_f(xb.x), hi_f(xb.x), lo_f(xb.y), hi_f(xb.y)}; v[2 * i + 1] = (f32x4){lo_f(xb.z), hi_f(xb.z), lo_f(xb.w), hi_f(xb.w)}; } }
; }
; __device__ void phase_norm(const Ctx& c, const void* xlat, bool lat_f32, const void* xctx, bool ctx_f32, const float* __restrict__ g, const float* __restrict__ mod, int sh_off, int sc_off,
;                            bf16_t* __restrict__ dst, int nrows, const float* part) {
;     bf16_t* XW = c.bfp(WS_XW);
;     for (int row = c.bid * 8 + c.wave; row < nrows; row += c.G * 8) {
;         f32x4 v[8];
;         if (row < TL) load_row32(v, xlat, lat_f32, (size_t)row * DM, c.lane); else load_row32(v, xctx, ctx_f32, (size_t)(row - TL) * DM, c.lane);
;         if (part != nullptr && row >= TL) {
;             const float* pr = part + (size_t)(row - TL) * DM + c.lane * 8; bf16_t* xo = XW + (size_t)row * DM + c.lane * 8;
; #pragma unroll
;             for (int i = 0; i < 4; ++i) {
; #pragma unroll
;                 for (int sp = 0; sp < 8; ++sp) { v[2 * i] += *(const f32x4*)(pr + (size_t)sp * TC * DM + i * 512); v[2 * i + 1] += *(const f32x4*)(pr + (size_t)sp * TC * DM + i * 512 + 4); }
;                 u32x4 w; w.x = cvt_pk_bf16(v[2 * i][0], v[2 * i][1]); w.y = cvt_pk_bf16(v[2 * i][2], v[2 * i][3]); w.z = cvt_pk_bf16(v[2 * i + 1][0], v[2 * i + 1][1]); w.w = cvt_pk_bf16(v[2 * i + 1][2], v[2 * i + 1][3]);
;                 *(u32x4*)(xo + i * 512) = w;
;                 __builtin_amdgcn_sched_barrier(0); }
.LBB0_1180:
	v_add_u32_e32 v12, 0xffffe000, v30
	v_cmp_gt_i32_e32 vcc, s86, v30
	s_movk_i32 s40, 0x1fff
	s_nop 0
	v_cndmask_b32_e32 v1, 0, v31, vcc
	v_cndmask_b32_e32 v0, v12, v30, vcc
	v_cndmask_b32_e32 v3, v15, v17, vcc
	v_cndmask_b32_e32 v2, v14, v16, vcc
	v_lshlrev_b64 v[0:1], 12, v[0:1]
	v_lshl_add_u64 v[34:35], v[2:3], 0, v[0:1]
	global_load_dwordx4 v[0:3], v[34:35], off
	global_load_dwordx4 v[4:7], v[34:35], off offset:1024
	global_load_dwordx4 v[8:11], v[34:35], off offset:2048
	global_load_dwordx4 v[66:69], v[34:35], off offset:3072
	v_cmp_lt_i32_e32 vcc, s40, v30
	s_waitcnt vmcnt(0)
	v_lshlrev_b32_e32 v64, 16, v0
	v_and_b32_e32 v65, 0xffff0000, v0
	v_lshlrev_b32_e32 v62, 16, v1
	v_and_b32_e32 v63, 0xffff0000, v1
	v_lshlrev_b32_e32 v60, 16, v2
	v_and_b32_e32 v61, 0xffff0000, v2
	v_lshlrev_b32_e32 v58, 16, v3
	v_and_b32_e32 v59, 0xffff0000, v3
	v_lshlrev_b32_e32 v56, 16, v4
	v_and_b32_e32 v57, 0xffff0000, v4
	v_lshlrev_b32_e32 v54, 16, v5
	v_and_b32_e32 v55, 0xffff0000, v5
	v_lshlrev_b32_e32 v52, 16, v6
	v_and_b32_e32 v53, 0xffff0000, v6
	v_lshlrev_b32_e32 v50, 16, v7
	v_and_b32_e32 v51, 0xffff0000, v7
	v_lshlrev_b32_e32 v46, 16, v8
	v_and_b32_e32 v47, 0xffff0000, v8
	v_lshlrev_b32_e32 v42, 16, v9
	v_and_b32_e32 v43, 0xffff0000, v9
	v_lshlrev_b32_e32 v48, 16, v10
	v_and_b32_e32 v49, 0xffff0000, v10
	v_lshlrev_b32_e32 v44, 16, v11
	v_and_b32_e32 v45, 0xffff0000, v11
	v_lshlrev_b32_e32 v40, 16, v66
	v_and_b32_e32 v41, 0xffff0000, v66
	v_lshlrev_b32_e32 v38, 16, v67
	v_and_b32_e32 v39, 0xffff0000, v67
	v_lshlrev_b32_e32 v36, 16, v68
	v_and_b32_e32 v37, 0xffff0000, v68
	v_lshlrev_b32_e32 v34, 16, v69
	v_and_b32_e32 v35, 0xffff0000, v69
	s_and_saveexec_b64 s[82:83], vcc
	s_cbranch_execz .LBB0_1179
	v_lshlrev_b64 v[0:1], 13, v[12:13]
	v_lshl_add_u64 v[2:3], v[18:19], 0, v[0:1]
	v_mov_b64_e32 v[170:171], v[2:3]
	v_mov_b32_e32 v173, 0
	v_mov_b32_e32 v172, 0x0
	v_lshl_add_u64 v[174:175], v[170:171], 0, v[172:173]
	global_load_dwordx4 v[106:109], v[174:175], off
	global_load_dwordx4 v[110:113], v[174:175], off offset:16
	v_mov_b32_e32 v172, 0x800000
	v_lshl_add_u64 v[174:175], v[170:171], 0, v[172:173]
	global_load_dwordx4 v[114:117], v[174:175], off
	global_load_dwordx4 v[118:121], v[174:175], off offset:16
	v_mov_b32_e32 v172, 0x1000000
	v_lshl_add_u64 v[174:175], v[170:171], 0, v[172:173]
	global_load_dwordx4 v[122:125], v[174:175], off
	global_load_dwordx4 v[126:129], v[174:175], off offset:16
	v_mov_b32_e32 v172, 0x1800000
	v_lshl_add_u64 v[174:175], v[170:171], 0, v[172:173]
	global_load_dwordx4 v[130:133], v[174:175], off
	global_load_dwordx4 v[134:137], v[174:175], off offset:16
	v_mov_b32_e32 v172, 0x2000000
	v_lshl_add_u64 v[174:175], v[170:171], 0, v[172:173]
	global_load_dwordx4 v[138:141], v[174:175], off
	global_load_dwordx4 v[142:145], v[174:175], off offset:16
	v_mov_b32_e32 v172, 0x2800000
	v_lshl_add_u64 v[174:175], v[170:171], 0, v[172:173]
	global_load_dwordx4 v[146:149], v[174:175], off
	global_load_dwordx4 v[150:153], v[174:175], off offset:16
	v_mov_b32_e32 v172, 0x3000000
	v_lshl_add_u64 v[174:175], v[170:171], 0, v[172:173]
	global_load_dwordx4 v[154:157], v[174:175], off
	global_load_dwordx4 v[158:161], v[174:175], off offset:16
	v_mov_b32_e32 v172, 0x3800000
	v_lshl_add_u64 v[174:175], v[170:171], 0, v[172:173]
	global_load_dwordx4 v[162:165], v[174:175], off
	global_load_dwordx4 v[166:169], v[174:175], off offset:16
	s_waitcnt vmcnt(0)
	v_mov_b64_e32 v[4:5], v[110:111]
	v_mov_b64_e32 v[6:7], v[112:113]
	v_mov_b64_e32 v[8:9], v[106:107]
	v_mov_b64_e32 v[10:11], v[108:109]
	v_add_co_u32_e32 v72, vcc, s87, v2
	s_mov_b64 s[44:45], 0x800000
	s_nop 0
	v_addc_co_u32_e32 v73, vcc, 0, v3, vcc
	s_mov_b32 s40, 0x1000000
	v_mov_b32_e32 v12, v30
	v_lshlrev_b64 v[0:1], 12, v[12:13]
	v_lshl_add_u64 v[0:1], v[16:17], 0, v[0:1]
	s_nop 0
	v_pk_add_f32 v[66:67], v[4:5], v[60:61]
	v_add_co_u32_e32 v4, vcc, s90, v2
	s_nop 0
	v_pk_add_f32 v[10:11], v[10:11], v[62:63]
	v_pk_add_f32 v[62:63], v[8:9], v[64:65]
	v_pk_add_f32 v[64:65], v[6:7], v[58:59]
	v_lshl_add_u64 v[58:59], v[2:3], 0, s[44:45]
	v_addc_co_u32_e32 v5, vcc, 0, v3, vcc
	v_mov_b64_e32 v[6:7], v[114:115]
	v_mov_b64_e32 v[8:9], v[116:117]
	s_nop 0
	v_mov_b64_e32 v[58:59], v[118:119]
	v_mov_b64_e32 v[60:61], v[120:121]
	v_add_co_u32_e32 v74, vcc, s40, v2
	s_mov_b64 s[44:45], 0x1000000
	s_nop 0
	v_addc_co_u32_e32 v75, vcc, 0, v3, vcc
	s_mov_b32 s40, 0x1800000
	s_nop 0
	v_pk_add_f32 v[62:63], v[62:63], v[6:7]
	v_add_co_u32_e32 v6, vcc, s91, v2
	s_nop 0
	v_pk_add_f32 v[66:67], v[66:67], v[58:59]
	v_lshl_add_u64 v[58:59], v[2:3], 0, s[44:45]
	v_addc_co_u32_e32 v7, vcc, 0, v3, vcc
	v_pk_add_f32 v[68:69], v[10:11], v[8:9]
	v_pk_add_f32 v[64:65], v[64:65], v[60:61]
	v_mov_b64_e32 v[8:9], v[122:123]
	v_mov_b64_e32 v[10:11], v[124:125]
	s_nop 0
	v_mov_b64_e32 v[58:59], v[126:127]
	v_mov_b64_e32 v[60:61], v[128:129]
	v_add_co_u32_e32 v76, vcc, s40, v2
	s_mov_b64 s[44:45], 0x1800000
	s_nop 0
	v_addc_co_u32_e32 v77, vcc, 0, v3, vcc
	s_brev_b32 s40, 64
	s_nop 0
	v_pk_add_f32 v[10:11], v[68:69], v[10:11]
	v_pk_add_f32 v[68:69], v[62:63], v[8:9]
	v_add_co_u32_e32 v8, vcc, s92, v2
	v_lshl_add_u64 v[62:63], v[2:3], 0, s[44:45]
	s_nop 0
	v_addc_co_u32_e32 v9, vcc, 0, v3, vcc
	s_nop 0
	v_pk_add_f32 v[70:71], v[64:65], v[60:61]
	v_pk_add_f32 v[66:67], v[66:67], v[58:59]
	v_mov_b64_e32 v[58:59], v[130:131]
	v_mov_b64_e32 v[60:61], v[132:133]
	s_nop 0
	v_mov_b64_e32 v[62:63], v[134:135]
	v_mov_b64_e32 v[64:65], v[136:137]
	v_add_co_u32_e32 v78, vcc, s40, v2
	s_mov_b64 s[44:45], 0x2000000
	s_nop 0
	v_addc_co_u32_e32 v79, vcc, 0, v3, vcc
	s_mov_b32 s40, 0x2800000
	s_nop 0
	v_pk_add_f32 v[80:81], v[10:11], v[60:61]
; __device__ __forceinline__ unsigned cvt_pk_bf16(float lo, float hi) { unsigned r; asm volatile("v_cvt_pk_bf16_f32 %0, %1, %2" : "=v"(r) : "v"(lo), "v"(hi)); return r; }
; __device__ void phase_norm(const Ctx& c, const void* xlat, bool lat_f32, const void* xctx, bool ctx_f32, const float* __restrict__ g, const float* __restrict__ mod, int sh_off, int sc_off,
;                            bf16_t* __restrict__ dst, int nrows, const float* part) {
;     ...
;         if (part != nullptr && row >= TL) {
;             const float* pr = part + (size_t)(row - TL) * DM + c.lane * 8; bf16_t* xo = XW + (size_t)row * DM + c.lane * 8;
; #pragma unroll
;             for (int i = 0; i < 4; ++i) {
; #pragma unroll
;                 for (int sp = 0; sp < 8; ++sp) { v[2 * i] += *(const f32x4*)(pr + (size_t)sp * TC * DM + i * 512); v[2 * i + 1] += *(const f32x4*)(pr + (size_t)sp * TC * DM + i * 512 + 4); }
;                 u32x4 w; w.x = cvt_pk_bf16(v[2 * i][0], v[2 * i][1]); w.y = cvt_pk_bf16(v[2 * i][2], v[2 * i][3]); w.z = cvt_pk_bf16(v[2 * i + 1][0], v[2 * i + 1][1]); w.w = cvt_pk_bf16(v[2 * i + 1][2], v[2 * i + 1][3]);
;                 *(u32x4*)(xo + i * 512) = w;
;                 __builtin_amdgcn_sched_barrier(0); }
	v_add_co_u32_e32 v10, vcc, s93, v2
	s_nop 0
	v_pk_add_f32 v[66:67], v[66:67], v[62:63]
	v_lshl_add_u64 v[62:63], v[2:3], 0, s[44:45]
	v_addc_co_u32_e32 v11, vcc, 0, v3, vcc
	v_pk_add_f32 v[68:69], v[68:69], v[58:59]
	v_pk_add_f32 v[70:71], v[70:71], v[64:65]
	v_mov_b64_e32 v[58:59], v[138:139]
	v_mov_b64_e32 v[60:61], v[140:141]
	s_nop 0
	v_mov_b64_e32 v[62:63], v[142:143]
	v_mov_b64_e32 v[64:65], v[144:145]
	s_mov_b64 s[44:45], 0x2800000
	s_nop 0
	v_pk_add_f32 v[82:83], v[80:81], v[60:61]
	v_add_co_u32_e32 v80, vcc, s40, v2
	s_nop 0
	v_pk_add_f32 v[84:85], v[66:67], v[62:63]
	v_addc_co_u32_e32 v81, vcc, 0, v3, vcc
	v_add_co_u32_e32 v66, vcc, s94, v2
	v_lshl_add_u64 v[62:63], v[2:3], 0, s[44:45]
	s_nop 0
	v_addc_co_u32_e32 v67, vcc, 0, v3, vcc
	v_pk_add_f32 v[68:69], v[68:69], v[58:59]
	v_pk_add_f32 v[70:71], v[70:71], v[64:65]
	v_mov_b64_e32 v[58:59], v[146:147]
	v_mov_b64_e32 v[60:61], v[148:149]
	s_nop 0
	v_mov_b64_e32 v[62:63], v[150:151]
	v_mov_b64_e32 v[64:65], v[152:153]
	s_mov_b32 s40, 0x3000000
	s_mov_b64 s[44:45], 0x3000000
	s_nop 0
	v_pk_add_f32 v[94:95], v[82:83], v[60:61]
	v_add_co_u32_e32 v82, vcc, s40, v2
	v_pk_add_f32 v[96:97], v[68:69], v[58:59]
	s_nop 0
	v_addc_co_u32_e32 v83, vcc, 0, v3, vcc
	v_add_co_u32_e32 v68, vcc, s95, v2
	s_nop 0
	v_pk_add_f32 v[84:85], v[84:85], v[62:63]
	v_lshl_add_u64 v[62:63], v[2:3], 0, s[44:45]
	v_addc_co_u32_e32 v69, vcc, 0, v3, vcc
	v_pk_add_f32 v[70:71], v[70:71], v[64:65]
	v_mov_b64_e32 v[58:59], v[154:155]
	v_mov_b64_e32 v[60:61], v[156:157]
	s_nop 0
	v_mov_b64_e32 v[62:63], v[158:159]
	v_mov_b64_e32 v[64:65], v[160:161]
	s_mov_b64 s[44:45], 0x3800000
	s_nop 0
	v_pk_add_f32 v[98:99], v[94:95], v[60:61]
	s_nop 0
	v_pk_add_f32 v[104:105], v[84:85], v[62:63]
	v_add_co_u32_e32 v84, vcc, s88, v2
	v_pk_add_f32 v[102:103], v[70:71], v[64:65]
	s_nop 0
	v_addc_co_u32_e32 v85, vcc, 0, v3, vcc
	v_add_co_u32_e32 v70, vcc, s96, v2
	v_pk_add_f32 v[100:101], v[96:97], v[58:59]
	s_nop 0
	v_addc_co_u32_e32 v71, vcc, 0, v3, vcc
	v_lshl_add_u64 v[62:63], v[2:3], 0, s[44:45]
	v_mov_b64_e32 v[58:59], v[162:163]
	v_mov_b64_e32 v[60:61], v[164:165]
	v_mov_b64_e32 v[94:95], v[166:167]
	v_mov_b64_e32 v[96:97], v[168:169]
	s_nop 0
	v_pk_add_f32 v[62:63], v[98:99], v[60:61]
	v_pk_add_f32 v[64:65], v[100:101], v[58:59]
	s_nop 0
	v_pk_add_f32 v[58:59], v[102:103], v[96:97]
	v_pk_add_f32 v[60:61], v[104:105], v[94:95]
	v_cvt_pk_bf16_f32 v94, v64, v65
	v_cvt_pk_bf16_f32 v95, v62, v63
	s_nop 0
	v_cvt_pk_bf16_f32 v96, v60, v61
	v_cvt_pk_bf16_f32 v97, v58, v59
	global_store_dwordx4 v[0:1], v[94:97], off
	v_mov_b32_e32 v172, 0x800
	v_lshl_add_u64 v[174:175], v[170:171], 0, v[172:173]
	global_load_dwordx4 v[106:109], v[174:175], off
	global_load_dwordx4 v[110:113], v[174:175], off offset:16
	v_mov_b32_e32 v172, 0x800800
	v_lshl_add_u64 v[174:175], v[170:171], 0, v[172:173]
	global_load_dwordx4 v[114:117], v[174:175], off
	global_load_dwordx4 v[118:121], v[174:175], off offset:16
	v_mov_b32_e32 v172, 0x1000800
	v_lshl_add_u64 v[174:175], v[170:171], 0, v[172:173]
	global_load_dwordx4 v[122:125], v[174:175], off
	global_load_dwordx4 v[126:129], v[174:175], off offset:16
	v_mov_b32_e32 v172, 0x1800800
	v_lshl_add_u64 v[174:175], v[170:171], 0, v[172:173]
	global_load_dwordx4 v[130:133], v[174:175], off
	global_load_dwordx4 v[134:137], v[174:175], off offset:16
	v_mov_b32_e32 v172, 0x2000800
	v_lshl_add_u64 v[174:175], v[170:171], 0, v[172:173]
	global_load_dwordx4 v[138:141], v[174:175], off
	global_load_dwordx4 v[142:145], v[174:175], off offset:16
	v_mov_b32_e32 v172, 0x2800800
	v_lshl_add_u64 v[174:175], v[170:171], 0, v[172:173]
	global_load_dwordx4 v[146:149], v[174:175], off
	global_load_dwordx4 v[150:153], v[174:175], off offset:16
	v_mov_b32_e32 v172, 0x3000800
	v_lshl_add_u64 v[174:175], v[170:171], 0, v[172:173]
	global_load_dwordx4 v[154:157], v[174:175], off
	global_load_dwordx4 v[158:161], v[174:175], off offset:16
	v_mov_b32_e32 v172, 0x3800800
	v_lshl_add_u64 v[174:175], v[170:171], 0, v[172:173]
	global_load_dwordx4 v[162:165], v[174:175], off
	global_load_dwordx4 v[166:169], v[174:175], off offset:16
	s_waitcnt vmcnt(0)
	v_mov_b64_e32 v[94:95], v[110:111]
	v_mov_b64_e32 v[96:97], v[112:113]
	s_nop 0
	v_mov_b64_e32 v[98:99], v[106:107]
	v_mov_b64_e32 v[100:101], v[108:109]
	s_nop 0
	v_pk_add_f32 v[96:97], v[96:97], v[50:51]
	s_nop 0
	v_pk_add_f32 v[100:101], v[100:101], v[54:55]
	v_lshl_add_u64 v[54:55], v[2:3], 0, s[24:25]
	v_pk_add_f32 v[98:99], v[98:99], v[56:57]
	v_pk_add_f32 v[94:95], v[94:95], v[52:53]
	v_mov_b64_e32 v[50:51], v[114:115]
	v_mov_b64_e32 v[52:53], v[116:117]
	s_nop 0
	v_mov_b64_e32 v[54:55], v[118:119]
	v_mov_b64_e32 v[56:57], v[120:121]
	s_nop 0
	v_pk_add_f32 v[72:73], v[100:101], v[52:53]
	s_nop 0
	v_pk_add_f32 v[94:95], v[94:95], v[54:55]
	v_lshl_add_u64 v[54:55], v[2:3], 0, s[26:27]
	v_pk_add_f32 v[98:99], v[98:99], v[50:51]
	v_pk_add_f32 v[96:97], v[96:97], v[56:57]
	v_mov_b64_e32 v[50:51], v[122:123]
	v_mov_b64_e32 v[52:53], v[124:125]
	s_nop 0
	v_mov_b64_e32 v[54:55], v[126:127]
	v_mov_b64_e32 v[56:57], v[128:129]
	s_nop 0
	v_pk_add_f32 v[72:73], v[72:73], v[52:53]
	s_nop 0
	v_pk_add_f32 v[94:95], v[94:95], v[54:55]
	v_lshl_add_u64 v[54:55], v[2:3], 0, s[28:29]
	v_pk_add_f32 v[74:75], v[98:99], v[50:51]
	v_pk_add_f32 v[96:97], v[96:97], v[56:57]
	v_mov_b64_e32 v[50:51], v[130:131]
	v_mov_b64_e32 v[52:53], v[132:133]
	s_nop 0
	v_mov_b64_e32 v[54:55], v[134:135]
	v_mov_b64_e32 v[56:57], v[136:137]
	s_nop 0
	v_pk_add_f32 v[72:73], v[72:73], v[52:53]
	s_nop 0
	v_pk_add_f32 v[94:95], v[94:95], v[54:55]
	v_lshl_add_u64 v[54:55], v[2:3], 0, s[30:31]
	v_pk_add_f32 v[74:75], v[74:75], v[50:51]
; __device__ __forceinline__ unsigned cvt_pk_bf16(float lo, float hi) { unsigned r; asm volatile("v_cvt_pk_bf16_f32 %0, %1, %2" : "=v"(r) : "v"(lo), "v"(hi)); return r; }
; __device__ void phase_norm(const Ctx& c, const void* xlat, bool lat_f32, const void* xctx, bool ctx_f32, const float* __restrict__ g, const float* __restrict__ mod, int sh_off, int sc_off,
;                            bf16_t* __restrict__ dst, int nrows, const float* part) {
;     ...
;         if (part != nullptr && row >= TL) {
;             const float* pr = part + (size_t)(row - TL) * DM + c.lane * 8; bf16_t* xo = XW + (size_t)row * DM + c.lane * 8;
; #pragma unroll
;             for (int i = 0; i < 4; ++i) {
; #pragma unroll
;                 for (int sp = 0; sp < 8; ++sp) { v[2 * i] += *(const f32x4*)(pr + (size_t)sp * TC * DM + i * 512); v[2 * i + 1] += *(const f32x4*)(pr + (size_t)sp * TC * DM + i * 512 + 4); }
;                 u32x4 w; w.x = cvt_pk_bf16(v[2 * i][0], v[2 * i][1]); w.y = cvt_pk_bf16(v[2 * i][2], v[2 * i][3]); w.z = cvt_pk_bf16(v[2 * i + 1][0], v[2 * i + 1][1]); w.w = cvt_pk_bf16(v[2 * i + 1][2], v[2 * i + 1][3]);
;                 *(u32x4*)(xo + i * 512) = w;
;                 __builtin_amdgcn_sched_barrier(0); }
	v_pk_add_f32 v[76:77], v[96:97], v[56:57]
	v_mov_b64_e32 v[50:51], v[138:139]
	v_mov_b64_e32 v[52:53], v[140:141]
	s_nop 0
	v_mov_b64_e32 v[54:55], v[142:143]
	v_mov_b64_e32 v[56:57], v[144:145]
	s_nop 0
	v_pk_add_f32 v[72:73], v[72:73], v[52:53]
	s_nop 0
	v_pk_add_f32 v[78:79], v[94:95], v[54:55]
	v_lshl_add_u64 v[54:55], v[2:3], 0, s[34:35]
	v_pk_add_f32 v[74:75], v[74:75], v[50:51]
	v_pk_add_f32 v[76:77], v[76:77], v[56:57]
	v_mov_b64_e32 v[50:51], v[146:147]
	v_mov_b64_e32 v[52:53], v[148:149]
	s_nop 0
	v_mov_b64_e32 v[54:55], v[150:151]
	v_mov_b64_e32 v[56:57], v[152:153]
	s_nop 0
	v_pk_add_f32 v[72:73], v[72:73], v[52:53]
	s_nop 0
	v_pk_add_f32 v[78:79], v[78:79], v[54:55]
	v_lshl_add_u64 v[54:55], v[2:3], 0, s[46:47]
	v_pk_add_f32 v[74:75], v[74:75], v[50:51]
	v_pk_add_f32 v[76:77], v[76:77], v[56:57]
	v_mov_b64_e32 v[50:51], v[154:155]
	v_mov_b64_e32 v[52:53], v[156:157]
	s_nop 0
	v_mov_b64_e32 v[54:55], v[158:159]
	v_mov_b64_e32 v[56:57], v[160:161]
	s_nop 0
	v_pk_add_f32 v[80:81], v[72:73], v[52:53]
	v_pk_add_f32 v[82:83], v[74:75], v[50:51]
	s_nop 0
	v_pk_add_f32 v[78:79], v[78:79], v[54:55]
	v_lshl_add_u64 v[54:55], v[2:3], 0, s[48:49]
	v_mov_b64_e32 v[50:51], v[162:163]
	v_mov_b64_e32 v[52:53], v[164:165]
	v_mov_b64_e32 v[72:73], v[166:167]
	v_mov_b64_e32 v[74:75], v[168:169]
	v_pk_add_f32 v[76:77], v[76:77], v[56:57]
	s_nop 0
	v_pk_add_f32 v[54:55], v[80:81], v[52:53]
	v_pk_add_f32 v[56:57], v[82:83], v[50:51]
	s_nop 0
	v_pk_add_f32 v[50:51], v[76:77], v[74:75]
	v_pk_add_f32 v[52:53], v[78:79], v[72:73]
	v_cvt_pk_bf16_f32 v72, v56, v57
	v_cvt_pk_bf16_f32 v73, v54, v55
	s_nop 0
	v_cvt_pk_bf16_f32 v74, v52, v53
	v_cvt_pk_bf16_f32 v75, v50, v51
	global_store_dwordx4 v[0:1], v[72:75], off offset:1024
	s_nop 1
	v_add_co_u32_e32 v72, vcc, s89, v2
	v_lshl_add_u64 v[78:79], v[2:3], 0, s[50:51]
	s_nop 0
	v_addc_co_u32_e32 v73, vcc, 0, v3, vcc
	v_mov_b32_e32 v172, 0x1000
	v_lshl_add_u64 v[174:175], v[170:171], 0, v[172:173]
	global_load_dwordx4 v[106:109], v[174:175], off
	global_load_dwordx4 v[110:113], v[174:175], off offset:16
	v_mov_b32_e32 v172, 0x801000
	v_lshl_add_u64 v[174:175], v[170:171], 0, v[172:173]
	global_load_dwordx4 v[114:117], v[174:175], off
	global_load_dwordx4 v[118:121], v[174:175], off offset:16
	v_mov_b32_e32 v172, 0x1001000
	v_lshl_add_u64 v[174:175], v[170:171], 0, v[172:173]
	global_load_dwordx4 v[122:125], v[174:175], off
	global_load_dwordx4 v[126:129], v[174:175], off offset:16
	v_mov_b32_e32 v172, 0x1801000
	v_lshl_add_u64 v[174:175], v[170:171], 0, v[172:173]
	global_load_dwordx4 v[130:133], v[174:175], off
	global_load_dwordx4 v[134:137], v[174:175], off offset:16
	v_mov_b32_e32 v172, 0x2001000
	v_lshl_add_u64 v[174:175], v[170:171], 0, v[172:173]
	global_load_dwordx4 v[138:141], v[174:175], off
	global_load_dwordx4 v[142:145], v[174:175], off offset:16
	v_mov_b32_e32 v172, 0x2801000
	v_lshl_add_u64 v[174:175], v[170:171], 0, v[172:173]
	global_load_dwordx4 v[146:149], v[174:175], off
	global_load_dwordx4 v[150:153], v[174:175], off offset:16
	v_mov_b32_e32 v172, 0x3001000
	v_lshl_add_u64 v[174:175], v[170:171], 0, v[172:173]
	global_load_dwordx4 v[154:157], v[174:175], off
	global_load_dwordx4 v[158:161], v[174:175], off offset:16
	v_mov_b32_e32 v172, 0x3801000
	v_lshl_add_u64 v[174:175], v[170:171], 0, v[172:173]
	global_load_dwordx4 v[162:165], v[174:175], off
	global_load_dwordx4 v[166:169], v[174:175], off offset:16
	s_waitcnt vmcnt(0)
	v_mov_b64_e32 v[74:75], v[106:107]
	v_mov_b64_e32 v[76:77], v[108:109]
	s_nop 0
	v_mov_b64_e32 v[78:79], v[110:111]
	v_mov_b64_e32 v[80:81], v[112:113]
	s_nop 0
	v_pk_add_f32 v[74:75], v[74:75], v[46:47]
	v_lshl_add_u64 v[46:47], v[2:3], 0, s[52:53]
	v_pk_add_f32 v[76:77], v[76:77], v[42:43]
	s_nop 0
	v_pk_add_f32 v[80:81], v[80:81], v[44:45]
	v_pk_add_f32 v[78:79], v[78:79], v[48:49]
	v_mov_b64_e32 v[42:43], v[114:115]
	v_mov_b64_e32 v[44:45], v[116:117]
	s_nop 0
	v_mov_b64_e32 v[46:47], v[118:119]
	v_mov_b64_e32 v[48:49], v[120:121]
	s_nop 0
	v_pk_add_f32 v[76:77], v[76:77], v[44:45]
	s_nop 0
	v_pk_add_f32 v[78:79], v[78:79], v[46:47]
	v_lshl_add_u64 v[46:47], v[2:3], 0, s[54:55]
	v_pk_add_f32 v[74:75], v[74:75], v[42:43]
	v_pk_add_f32 v[80:81], v[80:81], v[48:49]
	v_mov_b64_e32 v[42:43], v[122:123]
	v_mov_b64_e32 v[44:45], v[124:125]
	s_nop 0
	v_mov_b64_e32 v[46:47], v[126:127]
	v_mov_b64_e32 v[48:49], v[128:129]
	s_nop 0
	v_pk_add_f32 v[76:77], v[76:77], v[44:45]
	s_nop 0
	v_pk_add_f32 v[78:79], v[78:79], v[46:47]
	v_lshl_add_u64 v[46:47], v[2:3], 0, s[56:57]
	v_pk_add_f32 v[74:75], v[74:75], v[42:43]
	v_pk_add_f32 v[80:81], v[80:81], v[48:49]
	v_mov_b64_e32 v[42:43], v[130:131]
	v_mov_b64_e32 v[44:45], v[132:133]
	s_nop 0
	v_mov_b64_e32 v[46:47], v[134:135]
	v_mov_b64_e32 v[48:49], v[136:137]
	s_nop 0
	v_pk_add_f32 v[76:77], v[76:77], v[44:45]
	s_nop 0
	v_pk_add_f32 v[78:79], v[78:79], v[46:47]
	v_lshl_add_u64 v[46:47], v[2:3], 0, s[58:59]
	v_pk_add_f32 v[74:75], v[74:75], v[42:43]
	v_pk_add_f32 v[80:81], v[80:81], v[48:49]
	v_mov_b64_e32 v[42:43], v[138:139]
	v_mov_b64_e32 v[44:45], v[140:141]
	s_nop 0
	v_mov_b64_e32 v[46:47], v[142:143]
	v_mov_b64_e32 v[48:49], v[144:145]
	s_nop 0
	v_pk_add_f32 v[76:77], v[76:77], v[44:45]
	s_nop 0
	v_pk_add_f32 v[78:79], v[78:79], v[46:47]
	v_lshl_add_u64 v[46:47], v[2:3], 0, s[60:61]
	v_pk_add_f32 v[74:75], v[74:75], v[42:43]
	v_pk_add_f32 v[80:81], v[80:81], v[48:49]
	v_mov_b64_e32 v[42:43], v[146:147]
	v_mov_b64_e32 v[44:45], v[148:149]
	s_nop 0
	v_mov_b64_e32 v[46:47], v[150:151]
	v_mov_b64_e32 v[48:49], v[152:153]
	s_nop 0
	v_pk_add_f32 v[76:77], v[76:77], v[44:45]
	s_nop 0
	v_pk_add_f32 v[78:79], v[78:79], v[46:47]
; __device__ __forceinline__ unsigned cvt_pk_bf16(float lo, float hi) { unsigned r; asm volatile("v_cvt_pk_bf16_f32 %0, %1, %2" : "=v"(r) : "v"(lo), "v"(hi)); return r; }
; __device__ void phase_norm(const Ctx& c, const void* xlat, bool lat_f32, const void* xctx, bool ctx_f32, const float* __restrict__ g, const float* __restrict__ mod, int sh_off, int sc_off,
;                            bf16_t* __restrict__ dst, int nrows, const float* part) {
;     ...
;         if (part != nullptr && row >= TL) {
;             const float* pr = part + (size_t)(row - TL) * DM + c.lane * 8; bf16_t* xo = XW + (size_t)row * DM + c.lane * 8;
; #pragma unroll
;             for (int i = 0; i < 4; ++i) {
; #pragma unroll
;                 for (int sp = 0; sp < 8; ++sp) { v[2 * i] += *(const f32x4*)(pr + (size_t)sp * TC * DM + i * 512); v[2 * i + 1] += *(const f32x4*)(pr + (size_t)sp * TC * DM + i * 512 + 4); }
;                 u32x4 w; w.x = cvt_pk_bf16(v[2 * i][0], v[2 * i][1]); w.y = cvt_pk_bf16(v[2 * i][2], v[2 * i][3]); w.z = cvt_pk_bf16(v[2 * i + 1][0], v[2 * i + 1][1]); w.w = cvt_pk_bf16(v[2 * i + 1][2], v[2 * i + 1][3]);
;                 *(u32x4*)(xo + i * 512) = w;
;                 __builtin_amdgcn_sched_barrier(0); }
;         }
	v_lshl_add_u64 v[46:47], v[2:3], 0, s[62:63]
	v_pk_add_f32 v[74:75], v[74:75], v[42:43]
	v_pk_add_f32 v[80:81], v[80:81], v[48:49]
	v_mov_b64_e32 v[42:43], v[154:155]
	v_mov_b64_e32 v[44:45], v[156:157]
	s_nop 0
	v_mov_b64_e32 v[46:47], v[158:159]
	v_mov_b64_e32 v[48:49], v[160:161]
	s_nop 0
	v_pk_add_f32 v[82:83], v[76:77], v[44:45]
	v_pk_add_f32 v[84:85], v[74:75], v[42:43]
	s_nop 0
	v_pk_add_f32 v[78:79], v[78:79], v[46:47]
	v_lshl_add_u64 v[42:43], v[2:3], 0, s[64:65]
	v_mov_b64_e32 v[44:45], v[162:163]
	v_mov_b64_e32 v[46:47], v[164:165]
	v_mov_b64_e32 v[74:75], v[166:167]
	v_mov_b64_e32 v[76:77], v[168:169]
	v_pk_add_f32 v[48:49], v[80:81], v[48:49]
	s_nop 0
	v_pk_add_f32 v[42:43], v[82:83], v[46:47]
	v_pk_add_f32 v[46:47], v[84:85], v[44:45]
	s_nop 0
	v_pk_add_f32 v[44:45], v[48:49], v[76:77]
	v_pk_add_f32 v[48:49], v[78:79], v[74:75]
	v_cvt_pk_bf16_f32 v74, v46, v47
	v_cvt_pk_bf16_f32 v75, v42, v43
	s_nop 0
	v_cvt_pk_bf16_f32 v76, v48, v49
	v_cvt_pk_bf16_f32 v77, v44, v45
	global_store_dwordx4 v[0:1], v[74:77], off offset:2048
	s_nop 1
	v_lshl_add_u64 v[76:77], v[2:3], 0, s[66:67]
	v_mov_b32_e32 v172, 0x1800
	v_lshl_add_u64 v[174:175], v[170:171], 0, v[172:173]
	global_load_dwordx4 v[106:109], v[174:175], off
	global_load_dwordx4 v[110:113], v[174:175], off offset:16
	v_mov_b32_e32 v172, 0x801800
	v_lshl_add_u64 v[174:175], v[170:171], 0, v[172:173]
	global_load_dwordx4 v[114:117], v[174:175], off
	global_load_dwordx4 v[118:121], v[174:175], off offset:16
	v_mov_b32_e32 v172, 0x1001800
	v_lshl_add_u64 v[174:175], v[170:171], 0, v[172:173]
	global_load_dwordx4 v[122:125], v[174:175], off
	global_load_dwordx4 v[126:129], v[174:175], off offset:16
	v_mov_b32_e32 v172, 0x1801800
	v_lshl_add_u64 v[174:175], v[170:171], 0, v[172:173]
	global_load_dwordx4 v[130:133], v[174:175], off
	global_load_dwordx4 v[134:137], v[174:175], off offset:16
	v_mov_b32_e32 v172, 0x2001800
	v_lshl_add_u64 v[174:175], v[170:171], 0, v[172:173]
	global_load_dwordx4 v[138:141], v[174:175], off
	global_load_dwordx4 v[142:145], v[174:175], off offset:16
	v_mov_b32_e32 v172, 0x2801800
	v_lshl_add_u64 v[174:175], v[170:171], 0, v[172:173]
	global_load_dwordx4 v[146:149], v[174:175], off
	global_load_dwordx4 v[150:153], v[174:175], off offset:16
	v_mov_b32_e32 v172, 0x3001800
	v_lshl_add_u64 v[174:175], v[170:171], 0, v[172:173]
	global_load_dwordx4 v[154:157], v[174:175], off
	global_load_dwordx4 v[158:161], v[174:175], off offset:16
	v_mov_b32_e32 v172, 0x3801800
	v_lshl_add_u64 v[174:175], v[170:171], 0, v[172:173]
	global_load_dwordx4 v[162:165], v[174:175], off
	global_load_dwordx4 v[166:169], v[174:175], off offset:16
	s_waitcnt vmcnt(0)
	v_mov_b64_e32 v[72:73], v[106:107]
	v_mov_b64_e32 v[74:75], v[108:109]
	s_nop 0
	v_mov_b64_e32 v[76:77], v[110:111]
	v_mov_b64_e32 v[78:79], v[112:113]
	s_nop 0
	v_pk_add_f32 v[74:75], v[74:75], v[38:39]
	v_lshl_add_u64 v[38:39], v[2:3], 0, s[68:69]
	v_pk_add_f32 v[72:73], v[72:73], v[40:41]
	s_nop 0
	v_pk_add_f32 v[78:79], v[78:79], v[34:35]
	v_pk_add_f32 v[76:77], v[76:77], v[36:37]
	v_mov_b64_e32 v[34:35], v[114:115]
	v_mov_b64_e32 v[36:37], v[116:117]
	s_nop 0
	v_mov_b64_e32 v[38:39], v[118:119]
	v_mov_b64_e32 v[40:41], v[120:121]
	s_nop 0
	v_pk_add_f32 v[72:73], v[72:73], v[34:35]
	v_lshl_add_u64 v[34:35], v[2:3], 0, s[70:71]
	v_pk_add_f32 v[74:75], v[74:75], v[36:37]
	v_mov_b64_e32 v[4:5], v[122:123]
	v_mov_b64_e32 v[6:7], v[124:125]
	s_nop 0
	v_mov_b64_e32 v[34:35], v[126:127]
	v_mov_b64_e32 v[36:37], v[128:129]
	s_nop 0
	v_pk_add_f32 v[38:39], v[76:77], v[38:39]
	v_pk_add_f32 v[40:41], v[78:79], v[40:41]
	s_nop 0
	v_pk_add_f32 v[74:75], v[74:75], v[6:7]
	s_nop 0
	v_pk_add_f32 v[38:39], v[38:39], v[34:35]
	v_lshl_add_u64 v[34:35], v[2:3], 0, s[72:73]
	v_pk_add_f32 v[72:73], v[72:73], v[4:5]
	v_pk_add_f32 v[40:41], v[40:41], v[36:37]
	v_mov_b64_e32 v[4:5], v[130:131]
	v_mov_b64_e32 v[6:7], v[132:133]
	s_nop 0
	v_mov_b64_e32 v[34:35], v[134:135]
	v_mov_b64_e32 v[36:37], v[136:137]
	v_lshl_add_u64 v[8:9], v[2:3], 0, s[74:75]
	s_nop 0
	v_pk_add_f32 v[74:75], v[74:75], v[6:7]
	v_pk_add_f32 v[72:73], v[72:73], v[4:5]
	v_mov_b64_e32 v[4:5], v[138:139]
	v_mov_b64_e32 v[6:7], v[140:141]
	s_nop 0
	v_mov_b64_e32 v[8:9], v[142:143]
	v_mov_b64_e32 v[10:11], v[144:145]
	s_nop 0
	v_pk_add_f32 v[34:35], v[38:39], v[34:35]
	v_pk_add_f32 v[36:37], v[40:41], v[36:37]
	s_nop 0
	v_pk_add_f32 v[38:39], v[74:75], v[6:7]
	s_nop 0
	v_pk_add_f32 v[34:35], v[34:35], v[8:9]
	v_lshl_add_u64 v[8:9], v[2:3], 0, s[76:77]
	v_pk_add_f32 v[40:41], v[72:73], v[4:5]
	v_pk_add_f32 v[36:37], v[36:37], v[10:11]
	v_mov_b64_e32 v[4:5], v[146:147]
	v_mov_b64_e32 v[6:7], v[148:149]
	s_nop 0
	v_mov_b64_e32 v[8:9], v[150:151]
	v_mov_b64_e32 v[10:11], v[152:153]
	s_nop 0
	v_pk_add_f32 v[38:39], v[38:39], v[6:7]
	s_nop 0
	v_pk_add_f32 v[34:35], v[34:35], v[8:9]
	v_lshl_add_u64 v[8:9], v[2:3], 0, s[78:79]
	v_pk_add_f32 v[40:41], v[40:41], v[4:5]
	v_pk_add_f32 v[36:37], v[36:37], v[10:11]
	v_mov_b64_e32 v[4:5], v[154:155]
	v_mov_b64_e32 v[6:7], v[156:157]
	s_nop 0
	v_mov_b64_e32 v[8:9], v[158:159]
	v_mov_b64_e32 v[10:11], v[160:161]
	s_nop 0
	v_pk_add_f32 v[38:39], v[38:39], v[6:7]
	v_lshl_add_u64 v[6:7], v[2:3], 0, s[80:81]
	v_pk_add_f32 v[40:41], v[40:41], v[4:5]
	s_nop 0
	v_pk_add_f32 v[10:11], v[36:37], v[10:11]
	v_pk_add_f32 v[36:37], v[34:35], v[8:9]
	v_mov_b64_e32 v[2:3], v[162:163]
	v_mov_b64_e32 v[4:5], v[164:165]
	s_nop 0
	v_mov_b64_e32 v[6:7], v[166:167]
	v_mov_b64_e32 v[8:9], v[168:169]
	s_waitcnt vmcnt(1)
	v_pk_add_f32 v[38:39], v[38:39], v[4:5]
	v_pk_add_f32 v[40:41], v[40:41], v[2:3]
	s_waitcnt vmcnt(0)
	v_pk_add_f32 v[34:35], v[10:11], v[8:9]
	v_pk_add_f32 v[36:37], v[36:37], v[6:7]
	v_cvt_pk_bf16_f32 v2, v40, v41
	v_cvt_pk_bf16_f32 v3, v38, v39
	s_nop 0
	v_cvt_pk_bf16_f32 v4, v36, v37
	v_cvt_pk_bf16_f32 v5, v34, v35
	global_store_dwordx4 v[0:1], v[2:5], off offset:3072
	s_branch .LBB0_1179
